# residual GEMMs: f32 tile loads/stores in whole 128-byte lines (lanes fr/fr^8 exchange a quad via DPP), residual preloaded into accumulators
# speedup vs baseline: 1.0016x; 1.0003x over previous
.LBB0_343:
	s_add_i32 s15, s55, -2
	s_add_u32 s48, s48, 0x80
	s_addc_u32 s49, s49, 0
	s_add_u32 s56, s50, 0x100
	s_addc_u32 s57, s51, 0
	s_mov_b32 s50, 0
	s_cmp_eq_u32 s58, 2
	s_cbranch_scc0 .Lrp_zero
	s_cmp_lt_i32 s88, 0
	s_cbranch_scc0 .Lrp_zero
	s_lshl_b32 s98, s54, 8
	s_add_i32 s98, s98, s86
	v_or_b32_e32 v130, s98, v188
	v_mov_b32_e32 v131, v1
	v_lshlrev_b64 v[130:131], 13, v[130:131]
	v_lshl_add_u64 v[130:131], s[18:19], 0, v[130:131]
	v_lshl_or_b32 v132, s23, 8, v225
	v_ashrrev_i32_e32 v133, 31, v132
	v_lshlrev_b64 v[132:133], 2, v[132:133]
	v_lshl_add_u64 v[134:135], v[130:131], 0, v[132:133]
	v_cmp_gt_u32_e32 vcc, 8, v188
	v_mov_b32_e32 v142, 0xffff0040
	v_mov_b32_e32 v143, -1
	v_mov_b32_e32 v146, 64
	v_mov_b32_e32 v147, 0x10000
	v_cndmask_b32_e32 v142, v142, v1, vcc
	v_cndmask_b32_e32 v143, v143, v1, vcc
	v_cndmask_b32_e32 v146, v146, v147, vcc
	v_mov_b32_e32 v147, v1
	v_lshl_add_u64 v[144:145], v[134:135], 0, v[142:143]
	v_lshl_add_u64 v[150:151], v[134:135], 0, v[146:147]
	global_load_dwordx4 v[126:129], v[144:145], off
	global_load_dwordx4 v[122:125], v[150:151], off
	global_load_dwordx4 v[110:113], v[144:145], off offset:512
	global_load_dwordx4 v[106:109], v[150:151], off offset:512
	s_mov_b32 s98, 0x20000
	s_mov_b32 s99, 0
	v_lshl_add_u64 v[136:137], v[144:145], 0, s[98:99]
	v_lshl_add_u64 v[148:149], v[150:151], 0, s[98:99]
	global_load_dwordx4 v[118:121], v[136:137], off
	global_load_dwordx4 v[114:117], v[148:149], off
	global_load_dwordx4 v[94:97], v[136:137], off offset:512
	global_load_dwordx4 v[90:93], v[148:149], off offset:512
	s_mov_b32 s98, 0x40000
	s_mov_b32 s99, 0
	v_lshl_add_u64 v[136:137], v[144:145], 0, s[98:99]
	v_lshl_add_u64 v[148:149], v[150:151], 0, s[98:99]
	global_load_dwordx4 v[102:105], v[136:137], off
	global_load_dwordx4 v[98:101], v[148:149], off
	global_load_dwordx4 v[78:81], v[136:137], off offset:512
	global_load_dwordx4 v[74:77], v[148:149], off offset:512
	s_mov_b32 s98, 0x60000
	s_mov_b32 s99, 0
	v_lshl_add_u64 v[136:137], v[144:145], 0, s[98:99]
	v_lshl_add_u64 v[148:149], v[150:151], 0, s[98:99]
	global_load_dwordx4 v[86:89], v[136:137], off
	global_load_dwordx4 v[82:85], v[148:149], off
	global_load_dwordx4 v[70:73], v[136:137], off offset:512
	global_load_dwordx4 v[66:69], v[148:149], off offset:512
	s_mov_b32 s98, 0x100000
	s_mov_b32 s99, 0
	v_lshl_add_u64 v[136:137], v[144:145], 0, s[98:99]
	v_lshl_add_u64 v[148:149], v[150:151], 0, s[98:99]
	global_load_dwordx4 v[62:65], v[136:137], off
	global_load_dwordx4 v[58:61], v[148:149], off
	global_load_dwordx4 v[46:49], v[136:137], off offset:512
	global_load_dwordx4 v[42:45], v[148:149], off offset:512
	s_mov_b32 s98, 0x120000
	s_mov_b32 s99, 0
	v_lshl_add_u64 v[136:137], v[144:145], 0, s[98:99]
	v_lshl_add_u64 v[148:149], v[150:151], 0, s[98:99]
	global_load_dwordx4 v[54:57], v[136:137], off
	global_load_dwordx4 v[50:53], v[148:149], off
	global_load_dwordx4 v[30:33], v[136:137], off offset:512
	global_load_dwordx4 v[26:29], v[148:149], off offset:512
	s_mov_b32 s98, 0x140000
	s_mov_b32 s99, 0
	v_lshl_add_u64 v[136:137], v[144:145], 0, s[98:99]
	v_lshl_add_u64 v[148:149], v[150:151], 0, s[98:99]
	global_load_dwordx4 v[38:41], v[136:137], off
	global_load_dwordx4 v[34:37], v[148:149], off
	global_load_dwordx4 v[14:17], v[136:137], off offset:512
	global_load_dwordx4 v[10:13], v[148:149], off offset:512
	s_mov_b32 s98, 0x160000
	s_mov_b32 s99, 0
	v_lshl_add_u64 v[136:137], v[144:145], 0, s[98:99]
	v_lshl_add_u64 v[148:149], v[150:151], 0, s[98:99]
	global_load_dwordx4 v[22:25], v[136:137], off
	global_load_dwordx4 v[18:21], v[148:149], off
	global_load_dwordx4 v[6:9], v[136:137], off offset:512
	global_load_dwordx4 v[2:5], v[148:149], off offset:512
	s_waitcnt vmcnt(0)
	v_mov_b32_e32 v138, v126
	v_mov_b32_e32 v139, v127
	v_mov_b32_e32 v140, v128
	v_mov_b32_e32 v141, v129
	v_mov_b32_dpp v126, v122 row_ror:8 row_mask:0xf bank_mask:0xc
	v_mov_b32_dpp v127, v123 row_ror:8 row_mask:0xf bank_mask:0xc
	v_mov_b32_dpp v128, v124 row_ror:8 row_mask:0xf bank_mask:0xc
	v_mov_b32_dpp v129, v125 row_ror:8 row_mask:0xf bank_mask:0xc
	v_mov_b32_dpp v122, v138 row_ror:8 row_mask:0xf bank_mask:0x3
	v_mov_b32_dpp v123, v139 row_ror:8 row_mask:0xf bank_mask:0x3
	v_mov_b32_dpp v124, v140 row_ror:8 row_mask:0xf bank_mask:0x3
	v_mov_b32_dpp v125, v141 row_ror:8 row_mask:0xf bank_mask:0x3
	v_mov_b32_e32 v138, v110
	v_mov_b32_e32 v139, v111
	v_mov_b32_e32 v140, v112
	v_mov_b32_e32 v141, v113
	v_mov_b32_dpp v110, v106 row_ror:8 row_mask:0xf bank_mask:0xc
	v_mov_b32_dpp v111, v107 row_ror:8 row_mask:0xf bank_mask:0xc
	v_mov_b32_dpp v112, v108 row_ror:8 row_mask:0xf bank_mask:0xc
	v_mov_b32_dpp v113, v109 row_ror:8 row_mask:0xf bank_mask:0xc
	v_mov_b32_dpp v106, v138 row_ror:8 row_mask:0xf bank_mask:0x3
	v_mov_b32_dpp v107, v139 row_ror:8 row_mask:0xf bank_mask:0x3
	v_mov_b32_dpp v108, v140 row_ror:8 row_mask:0xf bank_mask:0x3
	v_mov_b32_dpp v109, v141 row_ror:8 row_mask:0xf bank_mask:0x3
	v_mov_b32_e32 v138, v118
	v_mov_b32_e32 v139, v119
	v_mov_b32_e32 v140, v120
	v_mov_b32_e32 v141, v121
	v_mov_b32_dpp v118, v114 row_ror:8 row_mask:0xf bank_mask:0xc
	v_mov_b32_dpp v119, v115 row_ror:8 row_mask:0xf bank_mask:0xc
	v_mov_b32_dpp v120, v116 row_ror:8 row_mask:0xf bank_mask:0xc
	v_mov_b32_dpp v121, v117 row_ror:8 row_mask:0xf bank_mask:0xc
	v_mov_b32_dpp v114, v138 row_ror:8 row_mask:0xf bank_mask:0x3
	v_mov_b32_dpp v115, v139 row_ror:8 row_mask:0xf bank_mask:0x3
	v_mov_b32_dpp v116, v140 row_ror:8 row_mask:0xf bank_mask:0x3
	v_mov_b32_dpp v117, v141 row_ror:8 row_mask:0xf bank_mask:0x3
	v_mov_b32_e32 v138, v94
	v_mov_b32_e32 v139, v95
	v_mov_b32_e32 v140, v96
	v_mov_b32_e32 v141, v97
	v_mov_b32_dpp v94, v90 row_ror:8 row_mask:0xf bank_mask:0xc
	v_mov_b32_dpp v95, v91 row_ror:8 row_mask:0xf bank_mask:0xc
	v_mov_b32_dpp v96, v92 row_ror:8 row_mask:0xf bank_mask:0xc
	v_mov_b32_dpp v97, v93 row_ror:8 row_mask:0xf bank_mask:0xc
	v_mov_b32_dpp v90, v138 row_ror:8 row_mask:0xf bank_mask:0x3
	v_mov_b32_dpp v91, v139 row_ror:8 row_mask:0xf bank_mask:0x3
	v_mov_b32_dpp v92, v140 row_ror:8 row_mask:0xf bank_mask:0x3
	v_mov_b32_dpp v93, v141 row_ror:8 row_mask:0xf bank_mask:0x3
	v_mov_b32_e32 v138, v102
	v_mov_b32_e32 v139, v103
	v_mov_b32_e32 v140, v104
	v_mov_b32_e32 v141, v105
	v_mov_b32_dpp v102, v98 row_ror:8 row_mask:0xf bank_mask:0xc
	v_mov_b32_dpp v103, v99 row_ror:8 row_mask:0xf bank_mask:0xc
	v_mov_b32_dpp v104, v100 row_ror:8 row_mask:0xf bank_mask:0xc
	v_mov_b32_dpp v105, v101 row_ror:8 row_mask:0xf bank_mask:0xc
	v_mov_b32_dpp v98, v138 row_ror:8 row_mask:0xf bank_mask:0x3
	v_mov_b32_dpp v99, v139 row_ror:8 row_mask:0xf bank_mask:0x3
	v_mov_b32_dpp v100, v140 row_ror:8 row_mask:0xf bank_mask:0x3
	v_mov_b32_dpp v101, v141 row_ror:8 row_mask:0xf bank_mask:0x3
	v_mov_b32_e32 v138, v78
	v_mov_b32_e32 v139, v79
	v_mov_b32_e32 v140, v80
	v_mov_b32_e32 v141, v81
	v_mov_b32_dpp v78, v74 row_ror:8 row_mask:0xf bank_mask:0xc
	v_mov_b32_dpp v79, v75 row_ror:8 row_mask:0xf bank_mask:0xc
	v_mov_b32_dpp v80, v76 row_ror:8 row_mask:0xf bank_mask:0xc
	v_mov_b32_dpp v81, v77 row_ror:8 row_mask:0xf bank_mask:0xc
	v_mov_b32_dpp v74, v138 row_ror:8 row_mask:0xf bank_mask:0x3
	v_mov_b32_dpp v75, v139 row_ror:8 row_mask:0xf bank_mask:0x3
	v_mov_b32_dpp v76, v140 row_ror:8 row_mask:0xf bank_mask:0x3
	v_mov_b32_dpp v77, v141 row_ror:8 row_mask:0xf bank_mask:0x3
	v_mov_b32_e32 v138, v86
	v_mov_b32_e32 v139, v87
	v_mov_b32_e32 v140, v88
	v_mov_b32_e32 v141, v89
	v_mov_b32_dpp v86, v82 row_ror:8 row_mask:0xf bank_mask:0xc
	v_mov_b32_dpp v87, v83 row_ror:8 row_mask:0xf bank_mask:0xc
	v_mov_b32_dpp v88, v84 row_ror:8 row_mask:0xf bank_mask:0xc
	v_mov_b32_dpp v89, v85 row_ror:8 row_mask:0xf bank_mask:0xc
	v_mov_b32_dpp v82, v138 row_ror:8 row_mask:0xf bank_mask:0x3
	v_mov_b32_dpp v83, v139 row_ror:8 row_mask:0xf bank_mask:0x3
	v_mov_b32_dpp v84, v140 row_ror:8 row_mask:0xf bank_mask:0x3
	v_mov_b32_dpp v85, v141 row_ror:8 row_mask:0xf bank_mask:0x3
	v_mov_b32_e32 v138, v70
	v_mov_b32_e32 v139, v71
	v_mov_b32_e32 v140, v72
	v_mov_b32_e32 v141, v73
	v_mov_b32_dpp v70, v66 row_ror:8 row_mask:0xf bank_mask:0xc
	v_mov_b32_dpp v71, v67 row_ror:8 row_mask:0xf bank_mask:0xc
	v_mov_b32_dpp v72, v68 row_ror:8 row_mask:0xf bank_mask:0xc
	v_mov_b32_dpp v73, v69 row_ror:8 row_mask:0xf bank_mask:0xc
	v_mov_b32_dpp v66, v138 row_ror:8 row_mask:0xf bank_mask:0x3
	v_mov_b32_dpp v67, v139 row_ror:8 row_mask:0xf bank_mask:0x3
	v_mov_b32_dpp v68, v140 row_ror:8 row_mask:0xf bank_mask:0x3
	v_mov_b32_dpp v69, v141 row_ror:8 row_mask:0xf bank_mask:0x3
	v_mov_b32_e32 v138, v62
	v_mov_b32_e32 v139, v63
	v_mov_b32_e32 v140, v64
	v_mov_b32_e32 v141, v65
	v_mov_b32_dpp v62, v58 row_ror:8 row_mask:0xf bank_mask:0xc
	v_mov_b32_dpp v63, v59 row_ror:8 row_mask:0xf bank_mask:0xc
	v_mov_b32_dpp v64, v60 row_ror:8 row_mask:0xf bank_mask:0xc
	v_mov_b32_dpp v65, v61 row_ror:8 row_mask:0xf bank_mask:0xc
	v_mov_b32_dpp v58, v138 row_ror:8 row_mask:0xf bank_mask:0x3
	v_mov_b32_dpp v59, v139 row_ror:8 row_mask:0xf bank_mask:0x3
	v_mov_b32_dpp v60, v140 row_ror:8 row_mask:0xf bank_mask:0x3
	v_mov_b32_dpp v61, v141 row_ror:8 row_mask:0xf bank_mask:0x3
	v_mov_b32_e32 v138, v46
	v_mov_b32_e32 v139, v47
	v_mov_b32_e32 v140, v48
	v_mov_b32_e32 v141, v49
	v_mov_b32_dpp v46, v42 row_ror:8 row_mask:0xf bank_mask:0xc
	v_mov_b32_dpp v47, v43 row_ror:8 row_mask:0xf bank_mask:0xc
	v_mov_b32_dpp v48, v44 row_ror:8 row_mask:0xf bank_mask:0xc
	v_mov_b32_dpp v49, v45 row_ror:8 row_mask:0xf bank_mask:0xc
	v_mov_b32_dpp v42, v138 row_ror:8 row_mask:0xf bank_mask:0x3
	v_mov_b32_dpp v43, v139 row_ror:8 row_mask:0xf bank_mask:0x3
	v_mov_b32_dpp v44, v140 row_ror:8 row_mask:0xf bank_mask:0x3
	v_mov_b32_dpp v45, v141 row_ror:8 row_mask:0xf bank_mask:0x3
	v_mov_b32_e32 v138, v54
	v_mov_b32_e32 v139, v55
	v_mov_b32_e32 v140, v56
	v_mov_b32_e32 v141, v57
	v_mov_b32_dpp v54, v50 row_ror:8 row_mask:0xf bank_mask:0xc
	v_mov_b32_dpp v55, v51 row_ror:8 row_mask:0xf bank_mask:0xc
	v_mov_b32_dpp v56, v52 row_ror:8 row_mask:0xf bank_mask:0xc
	v_mov_b32_dpp v57, v53 row_ror:8 row_mask:0xf bank_mask:0xc
	v_mov_b32_dpp v50, v138 row_ror:8 row_mask:0xf bank_mask:0x3
	v_mov_b32_dpp v51, v139 row_ror:8 row_mask:0xf bank_mask:0x3
	v_mov_b32_dpp v52, v140 row_ror:8 row_mask:0xf bank_mask:0x3
	v_mov_b32_dpp v53, v141 row_ror:8 row_mask:0xf bank_mask:0x3
	v_mov_b32_e32 v138, v30
	v_mov_b32_e32 v139, v31
	v_mov_b32_e32 v140, v32
	v_mov_b32_e32 v141, v33
	v_mov_b32_dpp v30, v26 row_ror:8 row_mask:0xf bank_mask:0xc
	v_mov_b32_dpp v31, v27 row_ror:8 row_mask:0xf bank_mask:0xc
	v_mov_b32_dpp v32, v28 row_ror:8 row_mask:0xf bank_mask:0xc
	v_mov_b32_dpp v33, v29 row_ror:8 row_mask:0xf bank_mask:0xc
	v_mov_b32_dpp v26, v138 row_ror:8 row_mask:0xf bank_mask:0x3
	v_mov_b32_dpp v27, v139 row_ror:8 row_mask:0xf bank_mask:0x3
	v_mov_b32_dpp v28, v140 row_ror:8 row_mask:0xf bank_mask:0x3
	v_mov_b32_dpp v29, v141 row_ror:8 row_mask:0xf bank_mask:0x3
	v_mov_b32_e32 v138, v38
	v_mov_b32_e32 v139, v39
	v_mov_b32_e32 v140, v40
	v_mov_b32_e32 v141, v41
	v_mov_b32_dpp v38, v34 row_ror:8 row_mask:0xf bank_mask:0xc
	v_mov_b32_dpp v39, v35 row_ror:8 row_mask:0xf bank_mask:0xc
	v_mov_b32_dpp v40, v36 row_ror:8 row_mask:0xf bank_mask:0xc
	v_mov_b32_dpp v41, v37 row_ror:8 row_mask:0xf bank_mask:0xc
	v_mov_b32_dpp v34, v138 row_ror:8 row_mask:0xf bank_mask:0x3
	v_mov_b32_dpp v35, v139 row_ror:8 row_mask:0xf bank_mask:0x3
	v_mov_b32_dpp v36, v140 row_ror:8 row_mask:0xf bank_mask:0x3
	v_mov_b32_dpp v37, v141 row_ror:8 row_mask:0xf bank_mask:0x3
	v_mov_b32_e32 v138, v14
	v_mov_b32_e32 v139, v15
	v_mov_b32_e32 v140, v16
	v_mov_b32_e32 v141, v17
	v_mov_b32_dpp v14, v10 row_ror:8 row_mask:0xf bank_mask:0xc
	v_mov_b32_dpp v15, v11 row_ror:8 row_mask:0xf bank_mask:0xc
	v_mov_b32_dpp v16, v12 row_ror:8 row_mask:0xf bank_mask:0xc
	v_mov_b32_dpp v17, v13 row_ror:8 row_mask:0xf bank_mask:0xc
	v_mov_b32_dpp v10, v138 row_ror:8 row_mask:0xf bank_mask:0x3
	v_mov_b32_dpp v11, v139 row_ror:8 row_mask:0xf bank_mask:0x3
	v_mov_b32_dpp v12, v140 row_ror:8 row_mask:0xf bank_mask:0x3
	v_mov_b32_dpp v13, v141 row_ror:8 row_mask:0xf bank_mask:0x3
	v_mov_b32_e32 v138, v22
	v_mov_b32_e32 v139, v23
	v_mov_b32_e32 v140, v24
	v_mov_b32_e32 v141, v25
	v_mov_b32_dpp v22, v18 row_ror:8 row_mask:0xf bank_mask:0xc
	v_mov_b32_dpp v23, v19 row_ror:8 row_mask:0xf bank_mask:0xc
	v_mov_b32_dpp v24, v20 row_ror:8 row_mask:0xf bank_mask:0xc
	v_mov_b32_dpp v25, v21 row_ror:8 row_mask:0xf bank_mask:0xc
	v_mov_b32_dpp v18, v138 row_ror:8 row_mask:0xf bank_mask:0x3
	v_mov_b32_dpp v19, v139 row_ror:8 row_mask:0xf bank_mask:0x3
	v_mov_b32_dpp v20, v140 row_ror:8 row_mask:0xf bank_mask:0x3
	v_mov_b32_dpp v21, v141 row_ror:8 row_mask:0xf bank_mask:0x3
	v_mov_b32_e32 v138, v6
	v_mov_b32_e32 v139, v7
	v_mov_b32_e32 v140, v8
	v_mov_b32_e32 v141, v9
	v_mov_b32_dpp v6, v2 row_ror:8 row_mask:0xf bank_mask:0xc
	v_mov_b32_dpp v7, v3 row_ror:8 row_mask:0xf bank_mask:0xc
	v_mov_b32_dpp v8, v4 row_ror:8 row_mask:0xf bank_mask:0xc
	v_mov_b32_dpp v9, v5 row_ror:8 row_mask:0xf bank_mask:0xc
	v_mov_b32_dpp v2, v138 row_ror:8 row_mask:0xf bank_mask:0x3
	v_mov_b32_dpp v3, v139 row_ror:8 row_mask:0xf bank_mask:0x3
	v_mov_b32_dpp v4, v140 row_ror:8 row_mask:0xf bank_mask:0x3
	v_mov_b32_dpp v5, v141 row_ror:8 row_mask:0xf bank_mask:0x3
	s_branch .LBB0_344

.LBB0_374:
	s_and_b64 vcc, exec, s[48:49]
	s_cbranch_vccz .LBB0_387
	v_lshl_or_b32 v202, s23, 8, v225
	s_cmp_lt_i32 s88, 0
	s_mov_b64 s[48:49], -1
	v_ashrrev_i32_e32 v203, 31, v202
	v_add_u32_e32 v204, 0xffffe000, v196
	v_add_u32_e32 v200, 0xffffe010, v196
	v_add_u32_e32 v198, 0xffffe020, v196
	s_cbranch_scc0 .LBB0_385
	v_ashrrev_i32_e32 v197, 31, v196
	v_lshlrev_b64 v[130:131], 13, v[196:197]
	v_lshl_add_u64 v[130:131], s[78:79], 0, v[130:131]
	v_lshlrev_b64 v[206:207], 2, v[202:203]
	v_lshl_add_u64 v[134:135], v[130:131], 0, v[206:207]
	v_cmp_gt_u32_e32 vcc, 8, v188
	v_mov_b32_e32 v142, 0xffff0040
	v_mov_b32_e32 v143, -1
	v_mov_b32_e32 v146, 64
	v_mov_b32_e32 v147, 0x10000
	v_cndmask_b32_e32 v142, v142, v1, vcc
	v_cndmask_b32_e32 v143, v143, v1, vcc
	v_cndmask_b32_e32 v146, v146, v147, vcc
	v_mov_b32_e32 v147, v1
	v_lshl_add_u64 v[144:145], v[134:135], 0, v[142:143]
	v_lshl_add_u64 v[150:151], v[134:135], 0, v[146:147]
	v_mov_b32_e32 v138, v122
	v_mov_b32_e32 v139, v123
	v_mov_b32_e32 v140, v124
	v_mov_b32_e32 v141, v125
	v_mov_b32_dpp v122, v126 row_ror:8 row_mask:0xf bank_mask:0x3
	v_mov_b32_dpp v123, v127 row_ror:8 row_mask:0xf bank_mask:0x3
	v_mov_b32_dpp v124, v128 row_ror:8 row_mask:0xf bank_mask:0x3
	v_mov_b32_dpp v125, v129 row_ror:8 row_mask:0xf bank_mask:0x3
	v_mov_b32_dpp v126, v138 row_ror:8 row_mask:0xf bank_mask:0xc
	v_mov_b32_dpp v127, v139 row_ror:8 row_mask:0xf bank_mask:0xc
	v_mov_b32_dpp v128, v140 row_ror:8 row_mask:0xf bank_mask:0xc
	v_mov_b32_dpp v129, v141 row_ror:8 row_mask:0xf bank_mask:0xc
	global_store_dwordx4 v[144:145], v[126:129], off
	global_store_dwordx4 v[150:151], v[122:125], off
	v_mov_b32_e32 v138, v106
	v_mov_b32_e32 v139, v107
	v_mov_b32_e32 v140, v108
	v_mov_b32_e32 v141, v109
	v_mov_b32_dpp v106, v110 row_ror:8 row_mask:0xf bank_mask:0x3
	v_mov_b32_dpp v107, v111 row_ror:8 row_mask:0xf bank_mask:0x3
	v_mov_b32_dpp v108, v112 row_ror:8 row_mask:0xf bank_mask:0x3
	v_mov_b32_dpp v109, v113 row_ror:8 row_mask:0xf bank_mask:0x3
	v_mov_b32_dpp v110, v138 row_ror:8 row_mask:0xf bank_mask:0xc
	v_mov_b32_dpp v111, v139 row_ror:8 row_mask:0xf bank_mask:0xc
	v_mov_b32_dpp v112, v140 row_ror:8 row_mask:0xf bank_mask:0xc
	v_mov_b32_dpp v113, v141 row_ror:8 row_mask:0xf bank_mask:0xc
	global_store_dwordx4 v[144:145], v[110:113], off offset:512
	global_store_dwordx4 v[150:151], v[106:109], off offset:512
	s_mov_b32 s98, 0x20000
	s_mov_b32 s99, 0
	v_lshl_add_u64 v[136:137], v[144:145], 0, s[98:99]
	v_lshl_add_u64 v[148:149], v[150:151], 0, s[98:99]
	v_mov_b32_e32 v138, v114
	v_mov_b32_e32 v139, v115
	v_mov_b32_e32 v140, v116
	v_mov_b32_e32 v141, v117
	v_mov_b32_dpp v114, v118 row_ror:8 row_mask:0xf bank_mask:0x3
	v_mov_b32_dpp v115, v119 row_ror:8 row_mask:0xf bank_mask:0x3
	v_mov_b32_dpp v116, v120 row_ror:8 row_mask:0xf bank_mask:0x3
	v_mov_b32_dpp v117, v121 row_ror:8 row_mask:0xf bank_mask:0x3
	v_mov_b32_dpp v118, v138 row_ror:8 row_mask:0xf bank_mask:0xc
	v_mov_b32_dpp v119, v139 row_ror:8 row_mask:0xf bank_mask:0xc
	v_mov_b32_dpp v120, v140 row_ror:8 row_mask:0xf bank_mask:0xc
	v_mov_b32_dpp v121, v141 row_ror:8 row_mask:0xf bank_mask:0xc
	global_store_dwordx4 v[136:137], v[118:121], off
	global_store_dwordx4 v[148:149], v[114:117], off
	v_mov_b32_e32 v138, v90
	v_mov_b32_e32 v139, v91
	v_mov_b32_e32 v140, v92
	v_mov_b32_e32 v141, v93
	v_mov_b32_dpp v90, v94 row_ror:8 row_mask:0xf bank_mask:0x3
	v_mov_b32_dpp v91, v95 row_ror:8 row_mask:0xf bank_mask:0x3
	v_mov_b32_dpp v92, v96 row_ror:8 row_mask:0xf bank_mask:0x3
	v_mov_b32_dpp v93, v97 row_ror:8 row_mask:0xf bank_mask:0x3
	v_mov_b32_dpp v94, v138 row_ror:8 row_mask:0xf bank_mask:0xc
	v_mov_b32_dpp v95, v139 row_ror:8 row_mask:0xf bank_mask:0xc
	v_mov_b32_dpp v96, v140 row_ror:8 row_mask:0xf bank_mask:0xc
	v_mov_b32_dpp v97, v141 row_ror:8 row_mask:0xf bank_mask:0xc
	global_store_dwordx4 v[136:137], v[94:97], off offset:512
	global_store_dwordx4 v[148:149], v[90:93], off offset:512
	s_mov_b32 s98, 0x40000
	s_mov_b32 s99, 0
	v_lshl_add_u64 v[136:137], v[144:145], 0, s[98:99]
	v_lshl_add_u64 v[148:149], v[150:151], 0, s[98:99]
	v_mov_b32_e32 v138, v98
	v_mov_b32_e32 v139, v99
	v_mov_b32_e32 v140, v100
	v_mov_b32_e32 v141, v101
	v_mov_b32_dpp v98, v102 row_ror:8 row_mask:0xf bank_mask:0x3
	v_mov_b32_dpp v99, v103 row_ror:8 row_mask:0xf bank_mask:0x3
	v_mov_b32_dpp v100, v104 row_ror:8 row_mask:0xf bank_mask:0x3
	v_mov_b32_dpp v101, v105 row_ror:8 row_mask:0xf bank_mask:0x3
	v_mov_b32_dpp v102, v138 row_ror:8 row_mask:0xf bank_mask:0xc
	v_mov_b32_dpp v103, v139 row_ror:8 row_mask:0xf bank_mask:0xc
	v_mov_b32_dpp v104, v140 row_ror:8 row_mask:0xf bank_mask:0xc
	v_mov_b32_dpp v105, v141 row_ror:8 row_mask:0xf bank_mask:0xc
	global_store_dwordx4 v[136:137], v[102:105], off
	global_store_dwordx4 v[148:149], v[98:101], off
	v_mov_b32_e32 v138, v74
	v_mov_b32_e32 v139, v75
	v_mov_b32_e32 v140, v76
	v_mov_b32_e32 v141, v77
	v_mov_b32_dpp v74, v78 row_ror:8 row_mask:0xf bank_mask:0x3
	v_mov_b32_dpp v75, v79 row_ror:8 row_mask:0xf bank_mask:0x3
	v_mov_b32_dpp v76, v80 row_ror:8 row_mask:0xf bank_mask:0x3
	v_mov_b32_dpp v77, v81 row_ror:8 row_mask:0xf bank_mask:0x3
	v_mov_b32_dpp v78, v138 row_ror:8 row_mask:0xf bank_mask:0xc
	v_mov_b32_dpp v79, v139 row_ror:8 row_mask:0xf bank_mask:0xc
	v_mov_b32_dpp v80, v140 row_ror:8 row_mask:0xf bank_mask:0xc
	v_mov_b32_dpp v81, v141 row_ror:8 row_mask:0xf bank_mask:0xc
	global_store_dwordx4 v[136:137], v[78:81], off offset:512
	global_store_dwordx4 v[148:149], v[74:77], off offset:512
	s_mov_b32 s98, 0x60000
	s_mov_b32 s99, 0
	v_lshl_add_u64 v[136:137], v[144:145], 0, s[98:99]
	v_lshl_add_u64 v[148:149], v[150:151], 0, s[98:99]
	v_mov_b32_e32 v138, v82
	v_mov_b32_e32 v139, v83
	v_mov_b32_e32 v140, v84
	v_mov_b32_e32 v141, v85
	v_mov_b32_dpp v82, v86 row_ror:8 row_mask:0xf bank_mask:0x3
	v_mov_b32_dpp v83, v87 row_ror:8 row_mask:0xf bank_mask:0x3
	v_mov_b32_dpp v84, v88 row_ror:8 row_mask:0xf bank_mask:0x3
	v_mov_b32_dpp v85, v89 row_ror:8 row_mask:0xf bank_mask:0x3
	v_mov_b32_dpp v86, v138 row_ror:8 row_mask:0xf bank_mask:0xc
	v_mov_b32_dpp v87, v139 row_ror:8 row_mask:0xf bank_mask:0xc
	v_mov_b32_dpp v88, v140 row_ror:8 row_mask:0xf bank_mask:0xc
	v_mov_b32_dpp v89, v141 row_ror:8 row_mask:0xf bank_mask:0xc
	global_store_dwordx4 v[136:137], v[86:89], off
	global_store_dwordx4 v[148:149], v[82:85], off
	v_mov_b32_e32 v138, v66
	v_mov_b32_e32 v139, v67
	v_mov_b32_e32 v140, v68
	v_mov_b32_e32 v141, v69
	v_mov_b32_dpp v66, v70 row_ror:8 row_mask:0xf bank_mask:0x3
	v_mov_b32_dpp v67, v71 row_ror:8 row_mask:0xf bank_mask:0x3
	v_mov_b32_dpp v68, v72 row_ror:8 row_mask:0xf bank_mask:0x3
	v_mov_b32_dpp v69, v73 row_ror:8 row_mask:0xf bank_mask:0x3
	v_mov_b32_dpp v70, v138 row_ror:8 row_mask:0xf bank_mask:0xc
	v_mov_b32_dpp v71, v139 row_ror:8 row_mask:0xf bank_mask:0xc
	v_mov_b32_dpp v72, v140 row_ror:8 row_mask:0xf bank_mask:0xc
	v_mov_b32_dpp v73, v141 row_ror:8 row_mask:0xf bank_mask:0xc
	global_store_dwordx4 v[136:137], v[70:73], off offset:512
	global_store_dwordx4 v[148:149], v[66:69], off offset:512
	s_mov_b32 s98, 0x100000
	s_mov_b32 s99, 0
	v_lshl_add_u64 v[136:137], v[144:145], 0, s[98:99]
	v_lshl_add_u64 v[148:149], v[150:151], 0, s[98:99]
	v_mov_b32_e32 v138, v58
	v_mov_b32_e32 v139, v59
	v_mov_b32_e32 v140, v60
	v_mov_b32_e32 v141, v61
	v_mov_b32_dpp v58, v62 row_ror:8 row_mask:0xf bank_mask:0x3
	v_mov_b32_dpp v59, v63 row_ror:8 row_mask:0xf bank_mask:0x3
	v_mov_b32_dpp v60, v64 row_ror:8 row_mask:0xf bank_mask:0x3
	v_mov_b32_dpp v61, v65 row_ror:8 row_mask:0xf bank_mask:0x3
	v_mov_b32_dpp v62, v138 row_ror:8 row_mask:0xf bank_mask:0xc
	v_mov_b32_dpp v63, v139 row_ror:8 row_mask:0xf bank_mask:0xc
	v_mov_b32_dpp v64, v140 row_ror:8 row_mask:0xf bank_mask:0xc
	v_mov_b32_dpp v65, v141 row_ror:8 row_mask:0xf bank_mask:0xc
	global_store_dwordx4 v[136:137], v[62:65], off
	global_store_dwordx4 v[148:149], v[58:61], off
	v_mov_b32_e32 v138, v42
	v_mov_b32_e32 v139, v43
	v_mov_b32_e32 v140, v44
	v_mov_b32_e32 v141, v45
	v_mov_b32_dpp v42, v46 row_ror:8 row_mask:0xf bank_mask:0x3
	v_mov_b32_dpp v43, v47 row_ror:8 row_mask:0xf bank_mask:0x3
	v_mov_b32_dpp v44, v48 row_ror:8 row_mask:0xf bank_mask:0x3
	v_mov_b32_dpp v45, v49 row_ror:8 row_mask:0xf bank_mask:0x3
	v_mov_b32_dpp v46, v138 row_ror:8 row_mask:0xf bank_mask:0xc
	v_mov_b32_dpp v47, v139 row_ror:8 row_mask:0xf bank_mask:0xc
	v_mov_b32_dpp v48, v140 row_ror:8 row_mask:0xf bank_mask:0xc
	v_mov_b32_dpp v49, v141 row_ror:8 row_mask:0xf bank_mask:0xc
	global_store_dwordx4 v[136:137], v[46:49], off offset:512
	global_store_dwordx4 v[148:149], v[42:45], off offset:512
	s_mov_b32 s98, 0x120000
	s_mov_b32 s99, 0
	v_lshl_add_u64 v[136:137], v[144:145], 0, s[98:99]
	v_lshl_add_u64 v[148:149], v[150:151], 0, s[98:99]
	v_mov_b32_e32 v138, v50
	v_mov_b32_e32 v139, v51
	v_mov_b32_e32 v140, v52
	v_mov_b32_e32 v141, v53
	v_mov_b32_dpp v50, v54 row_ror:8 row_mask:0xf bank_mask:0x3
	v_mov_b32_dpp v51, v55 row_ror:8 row_mask:0xf bank_mask:0x3
	v_mov_b32_dpp v52, v56 row_ror:8 row_mask:0xf bank_mask:0x3
	v_mov_b32_dpp v53, v57 row_ror:8 row_mask:0xf bank_mask:0x3
	v_mov_b32_dpp v54, v138 row_ror:8 row_mask:0xf bank_mask:0xc
	v_mov_b32_dpp v55, v139 row_ror:8 row_mask:0xf bank_mask:0xc
	v_mov_b32_dpp v56, v140 row_ror:8 row_mask:0xf bank_mask:0xc
	v_mov_b32_dpp v57, v141 row_ror:8 row_mask:0xf bank_mask:0xc
	global_store_dwordx4 v[136:137], v[54:57], off
	global_store_dwordx4 v[148:149], v[50:53], off
	v_mov_b32_e32 v138, v26
	v_mov_b32_e32 v139, v27
	v_mov_b32_e32 v140, v28
	v_mov_b32_e32 v141, v29
	v_mov_b32_dpp v26, v30 row_ror:8 row_mask:0xf bank_mask:0x3
	v_mov_b32_dpp v27, v31 row_ror:8 row_mask:0xf bank_mask:0x3
	v_mov_b32_dpp v28, v32 row_ror:8 row_mask:0xf bank_mask:0x3
	v_mov_b32_dpp v29, v33 row_ror:8 row_mask:0xf bank_mask:0x3
	v_mov_b32_dpp v30, v138 row_ror:8 row_mask:0xf bank_mask:0xc
	v_mov_b32_dpp v31, v139 row_ror:8 row_mask:0xf bank_mask:0xc
	v_mov_b32_dpp v32, v140 row_ror:8 row_mask:0xf bank_mask:0xc
	v_mov_b32_dpp v33, v141 row_ror:8 row_mask:0xf bank_mask:0xc
	global_store_dwordx4 v[136:137], v[30:33], off offset:512
	global_store_dwordx4 v[148:149], v[26:29], off offset:512
	s_mov_b32 s98, 0x140000
	s_mov_b32 s99, 0
	v_lshl_add_u64 v[136:137], v[144:145], 0, s[98:99]
	v_lshl_add_u64 v[148:149], v[150:151], 0, s[98:99]
	v_mov_b32_e32 v138, v34
	v_mov_b32_e32 v139, v35
	v_mov_b32_e32 v140, v36
	v_mov_b32_e32 v141, v37
	v_mov_b32_dpp v34, v38 row_ror:8 row_mask:0xf bank_mask:0x3
	v_mov_b32_dpp v35, v39 row_ror:8 row_mask:0xf bank_mask:0x3
	v_mov_b32_dpp v36, v40 row_ror:8 row_mask:0xf bank_mask:0x3
	v_mov_b32_dpp v37, v41 row_ror:8 row_mask:0xf bank_mask:0x3
	v_mov_b32_dpp v38, v138 row_ror:8 row_mask:0xf bank_mask:0xc
	v_mov_b32_dpp v39, v139 row_ror:8 row_mask:0xf bank_mask:0xc
	v_mov_b32_dpp v40, v140 row_ror:8 row_mask:0xf bank_mask:0xc
	v_mov_b32_dpp v41, v141 row_ror:8 row_mask:0xf bank_mask:0xc
	global_store_dwordx4 v[136:137], v[38:41], off
	global_store_dwordx4 v[148:149], v[34:37], off
	v_mov_b32_e32 v138, v10
	v_mov_b32_e32 v139, v11
	v_mov_b32_e32 v140, v12
	v_mov_b32_e32 v141, v13
	v_mov_b32_dpp v10, v14 row_ror:8 row_mask:0xf bank_mask:0x3
	v_mov_b32_dpp v11, v15 row_ror:8 row_mask:0xf bank_mask:0x3
	v_mov_b32_dpp v12, v16 row_ror:8 row_mask:0xf bank_mask:0x3
	v_mov_b32_dpp v13, v17 row_ror:8 row_mask:0xf bank_mask:0x3
	v_mov_b32_dpp v14, v138 row_ror:8 row_mask:0xf bank_mask:0xc
	v_mov_b32_dpp v15, v139 row_ror:8 row_mask:0xf bank_mask:0xc
	v_mov_b32_dpp v16, v140 row_ror:8 row_mask:0xf bank_mask:0xc
	v_mov_b32_dpp v17, v141 row_ror:8 row_mask:0xf bank_mask:0xc
	global_store_dwordx4 v[136:137], v[14:17], off offset:512
	global_store_dwordx4 v[148:149], v[10:13], off offset:512
	s_mov_b32 s98, 0x160000
	s_mov_b32 s99, 0
	v_lshl_add_u64 v[136:137], v[144:145], 0, s[98:99]
	v_lshl_add_u64 v[148:149], v[150:151], 0, s[98:99]
	v_mov_b32_e32 v138, v18
	v_mov_b32_e32 v139, v19
	v_mov_b32_e32 v140, v20
	v_mov_b32_e32 v141, v21
	v_mov_b32_dpp v18, v22 row_ror:8 row_mask:0xf bank_mask:0x3
	v_mov_b32_dpp v19, v23 row_ror:8 row_mask:0xf bank_mask:0x3
	v_mov_b32_dpp v20, v24 row_ror:8 row_mask:0xf bank_mask:0x3
	v_mov_b32_dpp v21, v25 row_ror:8 row_mask:0xf bank_mask:0x3
	v_mov_b32_dpp v22, v138 row_ror:8 row_mask:0xf bank_mask:0xc
	v_mov_b32_dpp v23, v139 row_ror:8 row_mask:0xf bank_mask:0xc
	v_mov_b32_dpp v24, v140 row_ror:8 row_mask:0xf bank_mask:0xc
	v_mov_b32_dpp v25, v141 row_ror:8 row_mask:0xf bank_mask:0xc
	global_store_dwordx4 v[136:137], v[22:25], off
	global_store_dwordx4 v[148:149], v[18:21], off
	v_mov_b32_e32 v138, v2
	v_mov_b32_e32 v139, v3
	v_mov_b32_e32 v140, v4
	v_mov_b32_e32 v141, v5
	v_mov_b32_dpp v2, v6 row_ror:8 row_mask:0xf bank_mask:0x3
	v_mov_b32_dpp v3, v7 row_ror:8 row_mask:0xf bank_mask:0x3
	v_mov_b32_dpp v4, v8 row_ror:8 row_mask:0xf bank_mask:0x3
	v_mov_b32_dpp v5, v9 row_ror:8 row_mask:0xf bank_mask:0x3
	v_mov_b32_dpp v6, v138 row_ror:8 row_mask:0xf bank_mask:0xc
	v_mov_b32_dpp v7, v139 row_ror:8 row_mask:0xf bank_mask:0xc
	v_mov_b32_dpp v8, v140 row_ror:8 row_mask:0xf bank_mask:0xc
	v_mov_b32_dpp v9, v141 row_ror:8 row_mask:0xf bank_mask:0xc
	global_store_dwordx4 v[136:137], v[6:9], off offset:512
	global_store_dwordx4 v[148:149], v[2:5], off offset:512
	s_mov_b64 s[48:49], 0
.LBB0_385:
	s_and_b64 vcc, exec, s[48:49]
	s_cbranch_vccz .LBB0_387
	s_lshl_b64 s[48:49], s[88:89], 23
	v_ashrrev_i32_e32 v205, 31, v204
	s_add_u32 s48, s82, s48
	s_addc_u32 s49, s83, s49
	v_lshlrev_b64 v[130:131], 13, v[204:205]
	v_lshl_add_u64 v[130:131], s[48:49], 0, v[130:131]
	v_lshlrev_b64 v[132:133], 2, v[202:203]
	v_lshl_add_u64 v[134:135], v[130:131], 0, v[132:133]
	v_cmp_gt_u32_e32 vcc, 8, v188
	v_mov_b32_e32 v142, 0xffff0040
	v_mov_b32_e32 v143, -1
	v_mov_b32_e32 v146, 64
	v_mov_b32_e32 v147, 0x10000
	v_cndmask_b32_e32 v142, v142, v1, vcc
	v_cndmask_b32_e32 v143, v143, v1, vcc
	v_cndmask_b32_e32 v146, v146, v147, vcc
	v_mov_b32_e32 v147, v1
	v_lshl_add_u64 v[144:145], v[134:135], 0, v[142:143]
	v_lshl_add_u64 v[150:151], v[134:135], 0, v[146:147]
	v_mov_b32_e32 v138, v122
	v_mov_b32_e32 v139, v123
	v_mov_b32_e32 v140, v124
	v_mov_b32_e32 v141, v125
	v_mov_b32_dpp v122, v126 row_ror:8 row_mask:0xf bank_mask:0x3
	v_mov_b32_dpp v123, v127 row_ror:8 row_mask:0xf bank_mask:0x3
	v_mov_b32_dpp v124, v128 row_ror:8 row_mask:0xf bank_mask:0x3
	v_mov_b32_dpp v125, v129 row_ror:8 row_mask:0xf bank_mask:0x3
	v_mov_b32_dpp v126, v138 row_ror:8 row_mask:0xf bank_mask:0xc
	v_mov_b32_dpp v127, v139 row_ror:8 row_mask:0xf bank_mask:0xc
	v_mov_b32_dpp v128, v140 row_ror:8 row_mask:0xf bank_mask:0xc
	v_mov_b32_dpp v129, v141 row_ror:8 row_mask:0xf bank_mask:0xc
	global_store_dwordx4 v[144:145], v[126:129], off
	global_store_dwordx4 v[150:151], v[122:125], off
	v_mov_b32_e32 v138, v106
	v_mov_b32_e32 v139, v107
	v_mov_b32_e32 v140, v108
	v_mov_b32_e32 v141, v109
	v_mov_b32_dpp v106, v110 row_ror:8 row_mask:0xf bank_mask:0x3
	v_mov_b32_dpp v107, v111 row_ror:8 row_mask:0xf bank_mask:0x3
	v_mov_b32_dpp v108, v112 row_ror:8 row_mask:0xf bank_mask:0x3
	v_mov_b32_dpp v109, v113 row_ror:8 row_mask:0xf bank_mask:0x3
	v_mov_b32_dpp v110, v138 row_ror:8 row_mask:0xf bank_mask:0xc
	v_mov_b32_dpp v111, v139 row_ror:8 row_mask:0xf bank_mask:0xc
	v_mov_b32_dpp v112, v140 row_ror:8 row_mask:0xf bank_mask:0xc
	v_mov_b32_dpp v113, v141 row_ror:8 row_mask:0xf bank_mask:0xc
	global_store_dwordx4 v[144:145], v[110:113], off offset:512
	global_store_dwordx4 v[150:151], v[106:109], off offset:512
	s_mov_b32 s98, 0x20000
	s_mov_b32 s99, 0
	v_lshl_add_u64 v[136:137], v[144:145], 0, s[98:99]
	v_lshl_add_u64 v[148:149], v[150:151], 0, s[98:99]
	v_mov_b32_e32 v138, v114
	v_mov_b32_e32 v139, v115
	v_mov_b32_e32 v140, v116
	v_mov_b32_e32 v141, v117
	v_mov_b32_dpp v114, v118 row_ror:8 row_mask:0xf bank_mask:0x3
	v_mov_b32_dpp v115, v119 row_ror:8 row_mask:0xf bank_mask:0x3
	v_mov_b32_dpp v116, v120 row_ror:8 row_mask:0xf bank_mask:0x3
	v_mov_b32_dpp v117, v121 row_ror:8 row_mask:0xf bank_mask:0x3
	v_mov_b32_dpp v118, v138 row_ror:8 row_mask:0xf bank_mask:0xc
	v_mov_b32_dpp v119, v139 row_ror:8 row_mask:0xf bank_mask:0xc
	v_mov_b32_dpp v120, v140 row_ror:8 row_mask:0xf bank_mask:0xc
	v_mov_b32_dpp v121, v141 row_ror:8 row_mask:0xf bank_mask:0xc
	global_store_dwordx4 v[136:137], v[118:121], off
	global_store_dwordx4 v[148:149], v[114:117], off
	v_mov_b32_e32 v138, v90
	v_mov_b32_e32 v139, v91
	v_mov_b32_e32 v140, v92
	v_mov_b32_e32 v141, v93
	v_mov_b32_dpp v90, v94 row_ror:8 row_mask:0xf bank_mask:0x3
	v_mov_b32_dpp v91, v95 row_ror:8 row_mask:0xf bank_mask:0x3
	v_mov_b32_dpp v92, v96 row_ror:8 row_mask:0xf bank_mask:0x3
	v_mov_b32_dpp v93, v97 row_ror:8 row_mask:0xf bank_mask:0x3
	v_mov_b32_dpp v94, v138 row_ror:8 row_mask:0xf bank_mask:0xc
	v_mov_b32_dpp v95, v139 row_ror:8 row_mask:0xf bank_mask:0xc
	v_mov_b32_dpp v96, v140 row_ror:8 row_mask:0xf bank_mask:0xc
	v_mov_b32_dpp v97, v141 row_ror:8 row_mask:0xf bank_mask:0xc
	global_store_dwordx4 v[136:137], v[94:97], off offset:512
	global_store_dwordx4 v[148:149], v[90:93], off offset:512
	s_mov_b32 s98, 0x40000
	s_mov_b32 s99, 0
	v_lshl_add_u64 v[136:137], v[144:145], 0, s[98:99]
	v_lshl_add_u64 v[148:149], v[150:151], 0, s[98:99]
	v_mov_b32_e32 v138, v98
	v_mov_b32_e32 v139, v99
	v_mov_b32_e32 v140, v100
	v_mov_b32_e32 v141, v101
	v_mov_b32_dpp v98, v102 row_ror:8 row_mask:0xf bank_mask:0x3
	v_mov_b32_dpp v99, v103 row_ror:8 row_mask:0xf bank_mask:0x3
	v_mov_b32_dpp v100, v104 row_ror:8 row_mask:0xf bank_mask:0x3
	v_mov_b32_dpp v101, v105 row_ror:8 row_mask:0xf bank_mask:0x3
	v_mov_b32_dpp v102, v138 row_ror:8 row_mask:0xf bank_mask:0xc
	v_mov_b32_dpp v103, v139 row_ror:8 row_mask:0xf bank_mask:0xc
	v_mov_b32_dpp v104, v140 row_ror:8 row_mask:0xf bank_mask:0xc
	v_mov_b32_dpp v105, v141 row_ror:8 row_mask:0xf bank_mask:0xc
	global_store_dwordx4 v[136:137], v[102:105], off
	global_store_dwordx4 v[148:149], v[98:101], off
	v_mov_b32_e32 v138, v74
	v_mov_b32_e32 v139, v75
	v_mov_b32_e32 v140, v76
	v_mov_b32_e32 v141, v77
	v_mov_b32_dpp v74, v78 row_ror:8 row_mask:0xf bank_mask:0x3
	v_mov_b32_dpp v75, v79 row_ror:8 row_mask:0xf bank_mask:0x3
	v_mov_b32_dpp v76, v80 row_ror:8 row_mask:0xf bank_mask:0x3
	v_mov_b32_dpp v77, v81 row_ror:8 row_mask:0xf bank_mask:0x3
	v_mov_b32_dpp v78, v138 row_ror:8 row_mask:0xf bank_mask:0xc
	v_mov_b32_dpp v79, v139 row_ror:8 row_mask:0xf bank_mask:0xc
	v_mov_b32_dpp v80, v140 row_ror:8 row_mask:0xf bank_mask:0xc
	v_mov_b32_dpp v81, v141 row_ror:8 row_mask:0xf bank_mask:0xc
	global_store_dwordx4 v[136:137], v[78:81], off offset:512
	global_store_dwordx4 v[148:149], v[74:77], off offset:512
	s_mov_b32 s98, 0x60000
	s_mov_b32 s99, 0
	v_lshl_add_u64 v[136:137], v[144:145], 0, s[98:99]
	v_lshl_add_u64 v[148:149], v[150:151], 0, s[98:99]
	v_mov_b32_e32 v138, v82
	v_mov_b32_e32 v139, v83
	v_mov_b32_e32 v140, v84
	v_mov_b32_e32 v141, v85
	v_mov_b32_dpp v82, v86 row_ror:8 row_mask:0xf bank_mask:0x3
	v_mov_b32_dpp v83, v87 row_ror:8 row_mask:0xf bank_mask:0x3
	v_mov_b32_dpp v84, v88 row_ror:8 row_mask:0xf bank_mask:0x3
	v_mov_b32_dpp v85, v89 row_ror:8 row_mask:0xf bank_mask:0x3
	v_mov_b32_dpp v86, v138 row_ror:8 row_mask:0xf bank_mask:0xc
	v_mov_b32_dpp v87, v139 row_ror:8 row_mask:0xf bank_mask:0xc
	v_mov_b32_dpp v88, v140 row_ror:8 row_mask:0xf bank_mask:0xc
	v_mov_b32_dpp v89, v141 row_ror:8 row_mask:0xf bank_mask:0xc
	global_store_dwordx4 v[136:137], v[86:89], off
	global_store_dwordx4 v[148:149], v[82:85], off
	v_mov_b32_e32 v138, v66
	v_mov_b32_e32 v139, v67
	v_mov_b32_e32 v140, v68
	v_mov_b32_e32 v141, v69
	v_mov_b32_dpp v66, v70 row_ror:8 row_mask:0xf bank_mask:0x3
	v_mov_b32_dpp v67, v71 row_ror:8 row_mask:0xf bank_mask:0x3
	v_mov_b32_dpp v68, v72 row_ror:8 row_mask:0xf bank_mask:0x3
	v_mov_b32_dpp v69, v73 row_ror:8 row_mask:0xf bank_mask:0x3
	v_mov_b32_dpp v70, v138 row_ror:8 row_mask:0xf bank_mask:0xc
	v_mov_b32_dpp v71, v139 row_ror:8 row_mask:0xf bank_mask:0xc
	v_mov_b32_dpp v72, v140 row_ror:8 row_mask:0xf bank_mask:0xc
	v_mov_b32_dpp v73, v141 row_ror:8 row_mask:0xf bank_mask:0xc
	global_store_dwordx4 v[136:137], v[70:73], off offset:512
	global_store_dwordx4 v[148:149], v[66:69], off offset:512
	s_mov_b32 s98, 0x100000
	s_mov_b32 s99, 0
	v_lshl_add_u64 v[136:137], v[144:145], 0, s[98:99]
	v_lshl_add_u64 v[148:149], v[150:151], 0, s[98:99]
	v_mov_b32_e32 v138, v58
	v_mov_b32_e32 v139, v59
	v_mov_b32_e32 v140, v60
	v_mov_b32_e32 v141, v61
	v_mov_b32_dpp v58, v62 row_ror:8 row_mask:0xf bank_mask:0x3
	v_mov_b32_dpp v59, v63 row_ror:8 row_mask:0xf bank_mask:0x3
	v_mov_b32_dpp v60, v64 row_ror:8 row_mask:0xf bank_mask:0x3
	v_mov_b32_dpp v61, v65 row_ror:8 row_mask:0xf bank_mask:0x3
	v_mov_b32_dpp v62, v138 row_ror:8 row_mask:0xf bank_mask:0xc
	v_mov_b32_dpp v63, v139 row_ror:8 row_mask:0xf bank_mask:0xc
	v_mov_b32_dpp v64, v140 row_ror:8 row_mask:0xf bank_mask:0xc
	v_mov_b32_dpp v65, v141 row_ror:8 row_mask:0xf bank_mask:0xc
	global_store_dwordx4 v[136:137], v[62:65], off
	global_store_dwordx4 v[148:149], v[58:61], off
	v_mov_b32_e32 v138, v42
	v_mov_b32_e32 v139, v43
	v_mov_b32_e32 v140, v44
	v_mov_b32_e32 v141, v45
	v_mov_b32_dpp v42, v46 row_ror:8 row_mask:0xf bank_mask:0x3
	v_mov_b32_dpp v43, v47 row_ror:8 row_mask:0xf bank_mask:0x3
	v_mov_b32_dpp v44, v48 row_ror:8 row_mask:0xf bank_mask:0x3
	v_mov_b32_dpp v45, v49 row_ror:8 row_mask:0xf bank_mask:0x3
	v_mov_b32_dpp v46, v138 row_ror:8 row_mask:0xf bank_mask:0xc
	v_mov_b32_dpp v47, v139 row_ror:8 row_mask:0xf bank_mask:0xc
	v_mov_b32_dpp v48, v140 row_ror:8 row_mask:0xf bank_mask:0xc
	v_mov_b32_dpp v49, v141 row_ror:8 row_mask:0xf bank_mask:0xc
	global_store_dwordx4 v[136:137], v[46:49], off offset:512
	global_store_dwordx4 v[148:149], v[42:45], off offset:512
	s_mov_b32 s98, 0x120000
	s_mov_b32 s99, 0
	v_lshl_add_u64 v[136:137], v[144:145], 0, s[98:99]
	v_lshl_add_u64 v[148:149], v[150:151], 0, s[98:99]
	v_mov_b32_e32 v138, v50
	v_mov_b32_e32 v139, v51
	v_mov_b32_e32 v140, v52
	v_mov_b32_e32 v141, v53
	v_mov_b32_dpp v50, v54 row_ror:8 row_mask:0xf bank_mask:0x3
	v_mov_b32_dpp v51, v55 row_ror:8 row_mask:0xf bank_mask:0x3
	v_mov_b32_dpp v52, v56 row_ror:8 row_mask:0xf bank_mask:0x3
	v_mov_b32_dpp v53, v57 row_ror:8 row_mask:0xf bank_mask:0x3
	v_mov_b32_dpp v54, v138 row_ror:8 row_mask:0xf bank_mask:0xc
	v_mov_b32_dpp v55, v139 row_ror:8 row_mask:0xf bank_mask:0xc
	v_mov_b32_dpp v56, v140 row_ror:8 row_mask:0xf bank_mask:0xc
	v_mov_b32_dpp v57, v141 row_ror:8 row_mask:0xf bank_mask:0xc
	global_store_dwordx4 v[136:137], v[54:57], off
	global_store_dwordx4 v[148:149], v[50:53], off
	v_mov_b32_e32 v138, v26
	v_mov_b32_e32 v139, v27
	v_mov_b32_e32 v140, v28
	v_mov_b32_e32 v141, v29
	v_mov_b32_dpp v26, v30 row_ror:8 row_mask:0xf bank_mask:0x3
	v_mov_b32_dpp v27, v31 row_ror:8 row_mask:0xf bank_mask:0x3
	v_mov_b32_dpp v28, v32 row_ror:8 row_mask:0xf bank_mask:0x3
	v_mov_b32_dpp v29, v33 row_ror:8 row_mask:0xf bank_mask:0x3
	v_mov_b32_dpp v30, v138 row_ror:8 row_mask:0xf bank_mask:0xc
	v_mov_b32_dpp v31, v139 row_ror:8 row_mask:0xf bank_mask:0xc
	v_mov_b32_dpp v32, v140 row_ror:8 row_mask:0xf bank_mask:0xc
	v_mov_b32_dpp v33, v141 row_ror:8 row_mask:0xf bank_mask:0xc
	global_store_dwordx4 v[136:137], v[30:33], off offset:512
	global_store_dwordx4 v[148:149], v[26:29], off offset:512
	s_mov_b32 s98, 0x140000
	s_mov_b32 s99, 0
	v_lshl_add_u64 v[136:137], v[144:145], 0, s[98:99]
	v_lshl_add_u64 v[148:149], v[150:151], 0, s[98:99]
	v_mov_b32_e32 v138, v34
	v_mov_b32_e32 v139, v35
	v_mov_b32_e32 v140, v36
	v_mov_b32_e32 v141, v37
	v_mov_b32_dpp v34, v38 row_ror:8 row_mask:0xf bank_mask:0x3
	v_mov_b32_dpp v35, v39 row_ror:8 row_mask:0xf bank_mask:0x3
	v_mov_b32_dpp v36, v40 row_ror:8 row_mask:0xf bank_mask:0x3
	v_mov_b32_dpp v37, v41 row_ror:8 row_mask:0xf bank_mask:0x3
	v_mov_b32_dpp v38, v138 row_ror:8 row_mask:0xf bank_mask:0xc
	v_mov_b32_dpp v39, v139 row_ror:8 row_mask:0xf bank_mask:0xc
	v_mov_b32_dpp v40, v140 row_ror:8 row_mask:0xf bank_mask:0xc
	v_mov_b32_dpp v41, v141 row_ror:8 row_mask:0xf bank_mask:0xc
	global_store_dwordx4 v[136:137], v[38:41], off
	global_store_dwordx4 v[148:149], v[34:37], off
	v_mov_b32_e32 v138, v10
	v_mov_b32_e32 v139, v11
	v_mov_b32_e32 v140, v12
	v_mov_b32_e32 v141, v13
	v_mov_b32_dpp v10, v14 row_ror:8 row_mask:0xf bank_mask:0x3
	v_mov_b32_dpp v11, v15 row_ror:8 row_mask:0xf bank_mask:0x3
	v_mov_b32_dpp v12, v16 row_ror:8 row_mask:0xf bank_mask:0x3
	v_mov_b32_dpp v13, v17 row_ror:8 row_mask:0xf bank_mask:0x3
	v_mov_b32_dpp v14, v138 row_ror:8 row_mask:0xf bank_mask:0xc
	v_mov_b32_dpp v15, v139 row_ror:8 row_mask:0xf bank_mask:0xc
	v_mov_b32_dpp v16, v140 row_ror:8 row_mask:0xf bank_mask:0xc
	v_mov_b32_dpp v17, v141 row_ror:8 row_mask:0xf bank_mask:0xc
	global_store_dwordx4 v[136:137], v[14:17], off offset:512
	global_store_dwordx4 v[148:149], v[10:13], off offset:512
	s_mov_b32 s98, 0x160000
	s_mov_b32 s99, 0
	v_lshl_add_u64 v[136:137], v[144:145], 0, s[98:99]
	v_lshl_add_u64 v[148:149], v[150:151], 0, s[98:99]
	v_mov_b32_e32 v138, v18
	v_mov_b32_e32 v139, v19
	v_mov_b32_e32 v140, v20
	v_mov_b32_e32 v141, v21
	v_mov_b32_dpp v18, v22 row_ror:8 row_mask:0xf bank_mask:0x3
	v_mov_b32_dpp v19, v23 row_ror:8 row_mask:0xf bank_mask:0x3
	v_mov_b32_dpp v20, v24 row_ror:8 row_mask:0xf bank_mask:0x3
	v_mov_b32_dpp v21, v25 row_ror:8 row_mask:0xf bank_mask:0x3
	v_mov_b32_dpp v22, v138 row_ror:8 row_mask:0xf bank_mask:0xc
	v_mov_b32_dpp v23, v139 row_ror:8 row_mask:0xf bank_mask:0xc
	v_mov_b32_dpp v24, v140 row_ror:8 row_mask:0xf bank_mask:0xc
	v_mov_b32_dpp v25, v141 row_ror:8 row_mask:0xf bank_mask:0xc
	global_store_dwordx4 v[136:137], v[22:25], off
	global_store_dwordx4 v[148:149], v[18:21], off
	v_mov_b32_e32 v138, v2
	v_mov_b32_e32 v139, v3
	v_mov_b32_e32 v140, v4
	v_mov_b32_e32 v141, v5
	v_mov_b32_dpp v2, v6 row_ror:8 row_mask:0xf bank_mask:0x3
	v_mov_b32_dpp v3, v7 row_ror:8 row_mask:0xf bank_mask:0x3
	v_mov_b32_dpp v4, v8 row_ror:8 row_mask:0xf bank_mask:0x3
	v_mov_b32_dpp v5, v9 row_ror:8 row_mask:0xf bank_mask:0x3
	v_mov_b32_dpp v6, v138 row_ror:8 row_mask:0xf bank_mask:0xc
	v_mov_b32_dpp v7, v139 row_ror:8 row_mask:0xf bank_mask:0xc
	v_mov_b32_dpp v8, v140 row_ror:8 row_mask:0xf bank_mask:0xc
	v_mov_b32_dpp v9, v141 row_ror:8 row_mask:0xf bank_mask:0xc
	global_store_dwordx4 v[136:137], v[6:9], off offset:512
	global_store_dwordx4 v[148:149], v[2:5], off offset:512
